# pe_rows: next row's loads issued into a second register set before the current row's compute (2 rows in flight per wave)
# speedup vs baseline: 1.0111x; 1.0111x over previous
.LBB0_408:
	s_andn2_b64 vcc, exec, s[0:1]
	s_cbranch_vccnz .LBB0_726
	s_cmp_lt_i32 s21, 2
	s_mov_b64 s[0:1], -1
	s_cbranch_scc1 .LBB0_634
	s_cmp_lt_i32 s21, 3
	s_cbranch_scc1 .LBB0_520
	s_cmp_gt_i32 s21, 3
	s_cbranch_scc0 .LBB0_430
	s_cmpk_gt_i32 s66, 0x33ff
	s_cbranch_scc1 .LBB0_429
	s_mul_i32 s0, s30, 0x60
	s_ashr_i32 s1, s0, 31
	v_readlane_b32 s80, v255, 16
	s_lshl_b64 s[0:1], s[0:1], 2
	v_readlane_b32 s82, v255, 18
	v_readlane_b32 s83, v255, 19
	s_add_u32 s0, s82, s0
	v_and_b32_e32 v0, 7, v240
	s_addc_u32 s1, s83, s1
	s_waitcnt vmcnt(0)
	v_lshlrev_b32_e32 v6, 5, v0
	v_lshlrev_b32_e32 v23, 4, v0
	global_load_dwordx4 v[2:5], v6, s[0:1] offset:16
	s_nop 0
	global_load_dwordx4 v[6:9], v6, s[0:1]
	s_mov_b32 s2, s21
	global_load_dwordx4 v[10:13], v23, s[0:1] offset:256
	s_lshl_b32 s0, s30, 9
	s_ashr_i32 s1, s0, 31
	v_readlane_b32 s8, v255, 32
	s_lshl_b64 s[0:1], s[0:1], 2
	v_readlane_b32 s10, v255, 34
	v_readlane_b32 s11, v255, 35
	s_add_u32 s0, s10, s0
	s_addc_u32 s1, s11, s1
	v_lshlrev_b32_e32 v18, 5, v204
	global_load_dwordx4 v[14:17], v18, s[0:1]
	s_nop 0
	global_load_dwordx4 v[18:21], v18, s[0:1] offset:16
	v_and_b32_e32 v26, 64, v232
	v_xor_b32_e32 v25, 1, v232
	v_add_u32_e32 v26, 64, v26
	v_cmp_lt_i32_e32 vcc, v25, v26
	s_lshl_b32 s0, s27, 5
	v_readlane_b32 s1, v254, 27
	v_cndmask_b32_e32 v25, v232, v25, vcc
	v_lshlrev_b32_e32 v55, 2, v25
	v_xor_b32_e32 v25, 2, v232
	s_add_i32 s8, s1, s0
	s_lshl_b32 s0, s27, 9
	v_readlane_b32 s1, v254, 29
	v_readlane_b32 s21, v255, 45
	s_ashr_i32 s5, s30, 31
	v_cmp_lt_i32_e32 vcc, v25, v26
	s_add_i32 s6, s1, s0
	s_ashr_i32 s67, s66, 31
	s_mul_i32 s0, s66, 0x1a00
	s_mov_b32 s21, s2
	v_cndmask_b32_e32 v25, v232, v25, vcc
	s_mul_hi_i32 s1, s66, 0x1a00
	s_add_u32 s2, s0, 0x2690d00
	v_lshlrev_b32_e32 v24, 3, v0
	v_lshlrev_b32_e32 v54, 2, v0
	v_lshrrev_b32_e32 v0, 3, v204
	v_lshlrev_b32_e32 v70, 2, v25
	v_xor_b32_e32 v25, 4, v232
	s_addc_u32 s3, s1, 0
	v_cmp_lt_i32_e32 vcc, v25, v26
	v_mul_u32_u24_e32 v26, 0x60, v0
	s_add_u32 s0, s0, 0x2690000
	v_lshlrev_b32_e32 v0, 4, v240
	s_addc_u32 s1, s1, 0
	v_and_b32_e32 v0, 0x3f0, v0
	v_mov_b32_e32 v57, s3
	v_lshl_add_u64 v[58:59], s[0:1], 0, v[0:1]
	s_lshl_b64 s[0:1], s[66:67], 10
	s_mul_i32 s3, s66, 0x600
	v_readlane_b32 s9, v255, 33
	v_or_b32_e32 v56, s2, v24
	s_mul_hi_i32 s2, s66, 0x600
	s_add_u32 s7, s3, 0x12810080
	s_addc_u32 s9, s2, 0
	v_cndmask_b32_e32 v25, v232, v25, vcc
	s_add_u32 s3, s3, 0x12810000
	v_lshlrev_b32_e32 v71, 2, v25
	v_or_b32_e32 v60, s0, v0
	v_or_b32_e32 v24, s7, v24
	v_mov_b32_e32 v25, s9
	v_lshlrev_b32_e32 v0, 1, v26
	s_addc_u32 s2, s2, 0
	v_lshl_add_u64 v[62:63], v[24:25], 0, v[0:1]
	v_or_b32_e32 v24, s3, v23
	v_mov_b32_e32 v25, s2
	v_lshl_add_u64 v[64:65], v[24:25], 0, v[0:1]
	s_add_u32 s0, s0, 0x10e10000
	v_and_b32_e32 v0, 56, v240
	v_lshlrev_b32_e32 v22, 3, v204
	v_mov_b32_e32 v61, s1
	s_addc_u32 s1, s1, 0
	v_lshlrev_b32_e32 v0, 4, v0
	v_or3_b32 v66, s0, v0, v23
	v_mov_b32_e32 v67, s1
	v_lshlrev_b32_e32 v0, 1, v22
	s_mov_b32 s9, s66
	v_readlane_b32 s81, v255, 17
	v_readlane_b32 s84, v255, 20
	v_readlane_b32 s85, v255, 21
	v_readlane_b32 s86, v255, 22
	v_readlane_b32 s87, v255, 23
	v_readlane_b32 s88, v255, 24
	v_readlane_b32 s89, v255, 25
	v_readlane_b32 s90, v255, 26
	v_readlane_b32 s91, v255, 27
	v_readlane_b32 s92, v255, 28
	v_readlane_b32 s93, v255, 29
	v_readlane_b32 s94, v255, 30
	v_readlane_b32 s95, v255, 31
	v_readlane_b32 s12, v255, 36
	v_readlane_b32 s13, v255, 37
	v_readlane_b32 s14, v255, 38
	v_readlane_b32 s15, v255, 39
	v_readlane_b32 s16, v255, 40
	v_readlane_b32 s17, v255, 41
	v_readlane_b32 s18, v255, 42
	v_readlane_b32 s19, v255, 43
	v_readlane_b32 s20, v255, 44
	v_readlane_b32 s22, v255, 46
	v_readlane_b32 s23, v255, 47
	s_branch .LBB0_415
.LBB0_415:
	v_readlane_b32 s12, v249, 0
	v_readlane_b32 s18, v249, 6
	v_readlane_b32 s19, v249, 7
	s_cmpk_lt_i32 s9, 0x3000
	s_cselect_b64 s[0:1], -1, 0
	v_lshl_add_u64 v[22:23], s[18:19], 0, v[66:67]
	global_load_dwordx4 v[42:45], v[22:23], off
	s_cmpk_gt_i32 s9, 0x2fff
	s_mov_b64 s[2:3], -1
	v_readlane_b32 s13, v249, 1
	v_readlane_b32 s14, v249, 2
	v_readlane_b32 s15, v249, 3
	v_readlane_b32 s16, v249, 4
	v_readlane_b32 s17, v249, 5
	s_cbranch_scc0 .LBB0_417
	s_add_i32 s2, s9, 0xffffd000
	s_lshr_b32 s2, s2, 7
	s_and_b32 s2, s2, 0x1fffffc
	s_add_u32 s2, s2, s30
	s_addc_u32 s3, 0, s5
	v_readlane_b32 s80, v254, 48
	s_and_b32 s7, s8, 0x3fe0
	s_lshl_b64 s[2:3], s[2:3], 16
	v_readlane_b32 s86, v254, 54
	v_readlane_b32 s87, v254, 55
	s_add_u32 s2, s86, s2
	s_addc_u32 s3, s87, s3
	s_lshl_b32 s7, s7, 2
	s_add_u32 s2, s2, s7
	s_addc_u32 s3, s3, 0
	v_lshlrev_b32_e32 v22, 2, v54
	global_load_dwordx4 v[46:49], v22, s[2:3]
	v_readlane_b32 s81, v254, 49
	v_readlane_b32 s82, v254, 50
	v_readlane_b32 s83, v254, 51
	v_readlane_b32 s84, v254, 52
	v_readlane_b32 s85, v254, 53
	v_readlane_b32 s88, v254, 56
	v_readlane_b32 s89, v254, 57
	v_readlane_b32 s90, v254, 58
	v_readlane_b32 s91, v254, 59
	v_readlane_b32 s92, v254, 60
	v_readlane_b32 s93, v254, 61
	v_readlane_b32 s94, v254, 62
	v_readlane_b32 s95, v254, 63
	s_mov_b64 s[2:3], 0

.Lpe_loop:
	v_mov_b64_e32 v[102:103], v[62:63]
	v_mov_b64_e32 v[104:105], v[64:65]
	s_mov_b32 s100, s9
	v_readlane_b32 s0, v254, 28
	s_add_i32 s8, s8, s0
	v_readlane_b32 s0, v254, 23
	v_readlane_b32 s1, v254, 24
	v_readlane_b32 s2, v254, 30
	s_add_i32 s9, s9, s96
	v_lshl_add_u64 v[56:57], v[56:57], 0, s[0:1]
	v_lshl_add_u64 v[58:59], v[58:59], 0, s[0:1]
	v_readlane_b32 s0, v254, 25
	s_add_i32 s6, s6, s33
	v_readlane_b32 s3, v254, 31
	v_readlane_b32 s1, v254, 26
	s_cmpk_gt_i32 s9, 0x33ff
	v_lshl_add_u64 v[60:61], v[60:61], 0, s[2:3]
	v_lshl_add_u64 v[62:63], v[62:63], 0, s[0:1]
	v_lshl_add_u64 v[64:65], v[64:65], 0, s[0:1]
	v_lshl_add_u64 v[66:67], v[66:67], 0, s[2:3]
	s_cbranch_scc1 .Lpe_nonext
	v_readlane_b32 s12, v249, 0
	v_readlane_b32 s18, v249, 6
	v_readlane_b32 s19, v249, 7
	s_cmpk_lt_i32 s9, 0x3000
	s_cselect_b64 s[0:1], -1, 0
	v_lshl_add_u64 v[128:129], s[18:19], 0, v[66:67]
	global_load_dwordx4 v[106:109], v[128:129], off
	s_cmpk_gt_i32 s9, 0x2fff
	s_mov_b64 s[2:3], -1
	v_readlane_b32 s13, v249, 1
	v_readlane_b32 s14, v249, 2
	v_readlane_b32 s15, v249, 3
	v_readlane_b32 s16, v249, 4
	v_readlane_b32 s17, v249, 5
	s_cbranch_scc0 .Lpe_b417
	s_add_i32 s2, s9, 0xffffd000
	s_lshr_b32 s2, s2, 7
	s_and_b32 s2, s2, 0x1fffffc
	s_add_u32 s2, s2, s30
	s_addc_u32 s3, 0, s5
	v_readlane_b32 s80, v254, 48
	s_and_b32 s7, s8, 0x3fe0
	s_lshl_b64 s[2:3], s[2:3], 16
	v_readlane_b32 s86, v254, 54
	v_readlane_b32 s87, v254, 55
	s_add_u32 s2, s86, s2
	s_addc_u32 s3, s87, s3
	s_lshl_b32 s7, s7, 2
	s_add_u32 s2, s2, s7
	s_addc_u32 s3, s3, 0
	v_lshlrev_b32_e32 v128, 2, v54
	global_load_dwordx4 v[110:113], v128, s[2:3]
	v_readlane_b32 s81, v254, 49
	v_readlane_b32 s82, v254, 50
	v_readlane_b32 s83, v254, 51
	v_readlane_b32 s84, v254, 52
	v_readlane_b32 s85, v254, 53
	v_readlane_b32 s88, v254, 56
	v_readlane_b32 s89, v254, 57
	v_readlane_b32 s90, v254, 58
	v_readlane_b32 s91, v254, 59
	v_readlane_b32 s92, v254, 60
	v_readlane_b32 s93, v254, 61
	v_readlane_b32 s94, v254, 62
	v_readlane_b32 s95, v254, 63
	s_mov_b64 s[2:3], 0
.Lpe_b417:
	s_andn2_b64 vcc, exec, s[2:3]
	s_cbranch_vccnz .Lpe_b419
	v_lshl_add_u64 v[128:129], s[18:19], 0, v[56:57]
	global_load_dwordx2 v[114:115], v[128:129], off
.Lpe_b419:
	s_and_b32 s2, s9, 0xfffff000
	s_cmpk_eq_i32 s2, 0x2000
	v_mov_b32_e32 v128, 0
	v_mov_b32_e32 v116, 1.0
	s_cselect_b64 s[36:37], -1, 0
	s_cmpk_lg_i32 s2, 0x2000
	v_mov_b32_e32 v117, 0
	v_mov_b32_e32 v118, 1.0
	v_mov_b32_e32 v119, 0
	s_cbranch_scc1 .Lpe_b421
	s_and_b32 s2, s8, 0xffe0
	v_or_b32_e32 v129, s2, v54
	v_readlane_b32 s2, v250, 2
	v_lshlrev_b32_e32 v129, 2, v129
	v_readlane_b32 s3, v250, 3
	s_nop 4
	global_load_dwordx4 v[116:119], v129, s[2:3]
.Lpe_b421:
	v_cndmask_b32_e64 v129, 0, 1, s[0:1]
	v_cmp_ne_u32_e64 s[38:39], 1, v129
	s_andn2_b64 vcc, exec, s[0:1]
	v_lshl_add_u64 v[96:97], s[18:19], 0, v[60:61]
	v_mov_b32_e32 v129, 0
	v_mov_b32_e32 v130, 0
	v_mov_b32_e32 v131, 0
	v_mov_b32_e32 v124, 0
	v_mov_b32_e32 v125, 0
	v_mov_b32_e32 v126, 0
	v_mov_b32_e32 v127, 0
	v_mov_b32_e32 v120, 0
	v_mov_b32_e32 v121, 0
	v_mov_b32_e32 v122, 0
	v_mov_b32_e32 v123, 0
	s_cbranch_vccnz .Lpe_b423
	v_add_co_u32_e32 v128, vcc, 0xd490000, v96
	s_nop 0
	v_addc_co_u32_e32 v129, vcc, 0, v97, vcc
	v_add_co_u32_e32 v130, vcc, 0xe090000, v96
	v_addc_co_u32_e32 v131, vcc, 0, v97, vcc
	global_load_dwordx4 v[120:123], v[128:129], off
	global_load_dwordx4 v[124:127], v[130:131], off
	v_lshl_add_u64 v[128:129], s[18:19], 0, v[58:59]
	global_load_dwordx4 v[128:131], v[128:129], off
.Lpe_b423:
	v_cndmask_b32_e64 v133, 0, 1, s[36:37]
	v_mov_b32_e32 v132, 0
	v_cmp_ne_u32_e64 s[0:1], 1, v133
	s_andn2_b64 vcc, exec, s[36:37]
	v_mov_b32_e32 v133, 0
	v_mov_b32_e32 v134, 0
	v_mov_b32_e32 v135, 0
	v_mov_b32_e32 v136, 0
	v_mov_b32_e32 v137, 0
	v_mov_b32_e32 v138, 0
	v_mov_b32_e32 v139, 0
	s_cbranch_vccnz .Lpe_nonext
	s_mov_b32 s7, s4
	s_lshl_b64 s[2:3], s[6:7], 1
	s_add_u32 s2, s18, s2
	v_add_co_u32_e32 v132, vcc, 0x15f90000, v96
	s_addc_u32 s3, s19, s3
	s_nop 0
	v_addc_co_u32_e32 v133, vcc, 0, v97, vcc
	v_lshl_add_u64 v[134:135], s[2:3], 0, v[0:1]
	v_add_co_u32_e32 v136, vcc, 0x1c01c000, v134
	s_nop 0
	v_addc_co_u32_e32 v137, vcc, 0, v135, vcc
	global_load_dwordx4 v[132:135], v[132:133], off
	s_nop 0
	global_load_dwordx4 v[136:139], v[136:137], off
.Lpe_nonext:
	s_cmpk_lt_i32 s100, 0x3000
	s_cselect_b64 s[38:39], 0, -1
	s_and_b32 s2, s100, 0xfffff000
	s_cmpk_eq_i32 s2, 0x2000
	s_cselect_b64 s[36:37], -1, 0
	s_cselect_b64 s[0:1], 0, -1
	s_and_b64 vcc, exec, s[38:39]
	s_cbranch_vccnz .Lpe_kpe_done
	v_lshlrev_b32_e32 v46, 16, v90
	v_and_b32_e32 v47, 0xffff0000, v90
	v_lshlrev_b32_e32 v48, 16, v91
	v_and_b32_e32 v49, 0xffff0000, v91
.Lpe_kpe_done:
	v_mul_f32_e32 v84, v47, v47
	v_fmac_f32_e32 v84, v46, v46
	v_fmac_f32_e32 v84, v48, v48
	v_lshlrev_b32_e32 v82, 16, v42
	v_and_b32_e32 v83, 0xffff0000, v42
	v_fmac_f32_e32 v84, v49, v49
	v_lshlrev_b32_e32 v78, 16, v43
	v_and_b32_e32 v79, 0xffff0000, v43
	v_pk_mul_f32 v[42:43], v[82:83], v[82:83]
	v_pk_mul_f32 v[80:81], v[78:79], v[78:79]
	v_add_f32_e32 v42, v42, v84
	v_add_f32_e32 v42, v43, v42
	v_lshlrev_b32_e32 v76, 16, v44
	v_and_b32_e32 v77, 0xffff0000, v44
	v_add_f32_e32 v42, v80, v42
	v_lshlrev_b32_e32 v72, 16, v45
	v_and_b32_e32 v73, 0xffff0000, v45
	v_pk_mul_f32 v[44:45], v[76:77], v[76:77]
	v_add_f32_e32 v42, v81, v42
	v_add_f32_e32 v42, v44, v42
	v_pk_mul_f32 v[74:75], v[72:73], v[72:73]
	v_add_f32_e32 v42, v45, v42
	v_add_f32_e32 v42, v74, v42
	v_add_f32_e32 v42, v75, v42
	ds_bpermute_b32 v43, v55, v42
	s_and_b64 vcc, exec, s[38:39]
	s_waitcnt lgkmcnt(0)
	v_add_f32_e32 v42, v42, v43
	ds_bpermute_b32 v43, v70, v42
	s_waitcnt lgkmcnt(0)
	v_add_f32_e32 v42, v42, v43
	ds_bpermute_b32 v43, v71, v42
	s_waitcnt lgkmcnt(0)
	v_add_f32_e32 v42, v42, v43
	v_fmamk_f32 v42, v42, 0x3c2aaaab, v248
	v_rsq_f32_e32 v42, v42
	s_nop 0
	v_pk_mul_f32 v[74:75], v[8:9], v[42:43] op_sel_hi:[1,0]
	s_nop 0
	v_pk_mul_f32 v[74:75], v[74:75], v[78:79]
	v_pk_mul_f32 v[78:79], v[4:5], v[42:43] op_sel_hi:[1,0]
	v_pk_mul_f32 v[44:45], v[6:7], v[42:43] op_sel_hi:[1,0]
	v_pk_mul_f32 v[72:73], v[78:79], v[72:73]
	v_pk_mul_f32 v[78:79], v[10:11], v[42:43] op_sel_hi:[1,0]
	v_pk_mul_f32 v[80:81], v[2:3], v[42:43] op_sel_hi:[1,0]
	v_pk_mul_f32 v[46:47], v[46:47], v[78:79]
	v_pk_mul_f32 v[42:43], v[12:13], v[42:43] op_sel_hi:[1,0]
	v_pk_mul_f32 v[44:45], v[44:45], v[82:83]
	v_pk_mul_f32 v[42:43], v[48:49], v[42:43]
	v_pk_mul_f32 v[48:49], v[50:51], v[46:47] op_sel:[1,1] op_sel_hi:[0,1]
	v_pk_fma_f32 v[78:79], v[50:51], v[46:47], v[48:49] op_sel_hi:[1,0,1] neg_lo:[0,0,1] neg_hi:[0,0,1]
	v_pk_fma_f32 v[48:49], v[50:51], v[46:47], v[48:49] op_sel_hi:[1,0,1]
	v_pk_mul_f32 v[50:51], v[52:53], v[42:43] op_sel:[1,1] op_sel_hi:[0,1]
	v_pk_mul_f32 v[76:77], v[80:81], v[76:77]
	v_pk_fma_f32 v[80:81], v[52:53], v[42:43], v[50:51] op_sel_hi:[1,0,1] neg_lo:[0,0,1] neg_hi:[0,0,1]
	v_pk_fma_f32 v[50:51], v[52:53], v[42:43], v[50:51] op_sel_hi:[1,0,1]
	v_cndmask_b32_e64 v49, v47, v49, s[36:37]
	v_cndmask_b32_e64 v48, v43, v51, s[36:37]
	v_cndmask_b32_e64 v50, v42, v80, s[36:37]
	v_cndmask_b32_e64 v51, v46, v78, s[36:37]
	v_cvt_pk_bf16_f32 v42, v44, v45
	v_cvt_pk_bf16_f32 v43, v74, v75
	v_cvt_pk_bf16_f32 v44, v76, v77
	v_cvt_pk_bf16_f32 v45, v72, v73
	v_lshl_add_u64 v[46:47], s[18:19], 0, v[104:105]
	global_store_dwordx4 v[46:47], v[42:45], off
	s_nop 1
	v_cvt_pk_bf16_f32 v42, v51, v49
	v_cvt_pk_bf16_f32 v43, v50, v48
	v_lshl_add_u64 v[44:45], s[18:19], 0, v[102:103]
	global_store_dwordx2 v[44:45], v[42:43], off
	s_cbranch_vccnz .LBB0_427
	v_lshlrev_b32_e32 v42, 16, v38
	v_and_b32_e32 v43, 0xffff0000, v38
	v_lshlrev_b32_e32 v44, 16, v34
	v_and_b32_e32 v45, 0xffff0000, v34
	v_lshlrev_b32_e32 v38, 16, v39
	v_and_b32_e32 v39, 0xffff0000, v39
	v_lshlrev_b32_e32 v34, 16, v35
	v_and_b32_e32 v35, 0xffff0000, v35
	v_pk_add_f32 v[34:35], v[34:35], v[38:39]
	v_lshlrev_b32_e32 v38, 16, v23
	v_and_b32_e32 v39, 0xffff0000, v23
	v_pk_fma_f32 v[34:35], v[16:17], v[38:39], v[34:35]
	v_pk_add_f32 v[42:43], v[44:45], v[42:43]
	v_mul_f32_e32 v23, 0x3d372713, v34
	v_mul_f32_e32 v23, v34, v23
	v_fma_f32 v23, v34, v23, v34
	v_mul_f32_e32 v23, 0x3f4c422a, v23
	v_add_f32_e32 v23, v23, v23
	v_mul_f32_e32 v23, 0xbfb8aa3b, v23
	v_exp_f32_e32 v23, v23
	v_lshlrev_b32_e32 v44, 16, v22
	v_and_b32_e32 v45, 0xffff0000, v22
	v_pk_fma_f32 v[42:43], v[14:15], v[44:45], v[42:43]
	v_add_f32_e32 v23, 1.0, v23
	v_rcp_f32_e32 v38, v23
	v_mul_f32_e32 v23, 0x3d372713, v35
	v_mul_f32_e32 v23, v35, v23
	v_fma_f32 v23, v35, v23, v35
	v_mul_f32_e32 v23, 0x3f4c422a, v23
	v_add_f32_e32 v23, v23, v23
	v_mul_f32_e32 v23, 0xbfb8aa3b, v23
	v_exp_f32_e32 v23, v23
	v_mul_f32_e32 v22, 0x3d372713, v42
	v_mul_f32_e32 v22, v42, v22
	v_fma_f32 v22, v42, v22, v42
	v_add_f32_e32 v23, 1.0, v23
	v_rcp_f32_e32 v39, v23
	v_mul_f32_e32 v22, 0x3f4c422a, v22
	v_add_f32_e32 v22, v22, v22
	v_mul_f32_e32 v22, 0xbfb8aa3b, v22
	v_pk_mul_f32 v[34:35], v[34:35], v[38:39]
	v_lshlrev_b32_e32 v38, 16, v36
	v_cvt_pk_bf16_f32 v23, v34, v35
	v_lshlrev_b32_e32 v34, 16, v40
	v_and_b32_e32 v35, 0xffff0000, v40
	v_and_b32_e32 v39, 0xffff0000, v36
	v_pk_add_f32 v[34:35], v[38:39], v[34:35]
	v_lshlrev_b32_e32 v38, 16, v24
	v_and_b32_e32 v39, 0xffff0000, v24
	v_pk_fma_f32 v[34:35], v[18:19], v[38:39], v[34:35]
	v_lshlrev_b32_e32 v36, 16, v37
	v_mul_f32_e32 v24, 0x3d372713, v34
	v_mul_f32_e32 v24, v34, v24
	v_fma_f32 v24, v34, v24, v34
	v_mul_f32_e32 v24, 0x3f4c422a, v24
	v_add_f32_e32 v24, v24, v24
	v_mul_f32_e32 v24, 0xbfb8aa3b, v24
	v_exp_f32_e32 v24, v24
	v_and_b32_e32 v37, 0xffff0000, v37
	v_exp_f32_e32 v22, v22
	v_add_f32_e32 v24, 1.0, v24
	v_rcp_f32_e32 v38, v24
	v_mul_f32_e32 v24, 0x3d372713, v35
	v_mul_f32_e32 v24, v35, v24
	v_fma_f32 v24, v35, v24, v35
	v_mul_f32_e32 v24, 0x3f4c422a, v24
	v_add_f32_e32 v24, v24, v24
	v_mul_f32_e32 v24, 0xbfb8aa3b, v24
	v_exp_f32_e32 v24, v24
	v_add_f32_e32 v22, 1.0, v22
	v_rcp_f32_e32 v44, v22
	v_mul_f32_e32 v22, 0x3d372713, v43
	v_add_f32_e32 v24, 1.0, v24
	v_rcp_f32_e32 v39, v24
	v_mul_f32_e32 v22, v43, v22
	v_fma_f32 v22, v43, v22, v43
	v_mul_f32_e32 v22, 0x3f4c422a, v22
	v_pk_mul_f32 v[34:35], v[34:35], v[38:39]
	v_add_f32_e32 v22, v22, v22
	v_cvt_pk_bf16_f32 v24, v34, v35
	v_lshlrev_b32_e32 v34, 16, v41
	v_and_b32_e32 v35, 0xffff0000, v41
	v_pk_add_f32 v[34:35], v[36:37], v[34:35]
	v_lshlrev_b32_e32 v36, 16, v25
	v_and_b32_e32 v37, 0xffff0000, v25
	v_pk_fma_f32 v[34:35], v[20:21], v[36:37], v[34:35]
	v_mul_f32_e32 v22, 0xbfb8aa3b, v22
	v_mul_f32_e32 v25, 0x3d372713, v34
	v_mul_f32_e32 v25, v34, v25
	v_fma_f32 v25, v34, v25, v34
	v_mul_f32_e32 v25, 0x3f4c422a, v25
	v_add_f32_e32 v25, v25, v25
	v_mul_f32_e32 v25, 0xbfb8aa3b, v25
	v_exp_f32_e32 v25, v25
	v_exp_f32_e32 v22, v22
	v_add_f32_e32 v25, 1.0, v25
	v_rcp_f32_e32 v36, v25
	v_mul_f32_e32 v25, 0x3d372713, v35
	v_mul_f32_e32 v25, v35, v25
	v_fma_f32 v25, v35, v25, v35
	v_mul_f32_e32 v25, 0x3f4c422a, v25
	v_add_f32_e32 v25, v25, v25
	v_mul_f32_e32 v25, 0xbfb8aa3b, v25
	v_exp_f32_e32 v25, v25
	v_add_f32_e32 v22, 1.0, v22
	v_rcp_f32_e32 v45, v22
	v_add_f32_e32 v25, 1.0, v25
	v_rcp_f32_e32 v37, v25
	v_pk_mul_f32 v[42:43], v[42:43], v[44:45]
	v_pk_mul_f32 v[34:35], v[34:35], v[36:37]
	s_nop 0
	v_cvt_pk_bf16_f32 v25, v34, v35
	v_add_co_u32_e32 v34, vcc, 0xec90000, v68
	v_cvt_pk_bf16_f32 v22, v42, v43
	s_nop 0
	v_addc_co_u32_e32 v35, vcc, 0, v69, vcc
	global_store_dwordx4 v[34:35], v[22:25], off

.Lpe_rowend:
	s_cmpk_gt_i32 s9, 0x33ff
	s_cbranch_scc1 .LBB0_429
	s_waitcnt vmcnt(2)
	v_mov_b64_e32 v[22:23], v[128:129]
	v_mov_b64_e32 v[24:25], v[130:131]
	v_mov_b64_e32 v[26:27], v[132:133]
	v_mov_b64_e32 v[28:29], v[134:135]
	v_mov_b64_e32 v[30:31], v[136:137]
	v_mov_b64_e32 v[32:33], v[138:139]
	v_mov_b64_e32 v[34:35], v[124:125]
	v_mov_b64_e32 v[36:37], v[126:127]
	v_mov_b64_e32 v[38:39], v[120:121]
	v_mov_b64_e32 v[40:41], v[122:123]
	v_mov_b64_e32 v[42:43], v[106:107]
	v_mov_b64_e32 v[44:45], v[108:109]
	v_mov_b64_e32 v[46:47], v[110:111]
	v_mov_b64_e32 v[48:49], v[112:113]
	v_mov_b64_e32 v[50:51], v[116:117]
	v_mov_b64_e32 v[52:53], v[118:119]
	v_mov_b64_e32 v[68:69], v[96:97]
	v_mov_b64_e32 v[90:91], v[114:115]
	s_branch .Lpe_loop

	.amdhsa_kernel _Z8mega_fwd4Args
		.amdhsa_group_segment_fixed_size 0
		.amdhsa_private_segment_fixed_size 0
		.amdhsa_kernarg_size 552
		.amdhsa_user_sgpr_count 2
		.amdhsa_user_sgpr_dispatch_ptr 0
		.amdhsa_user_sgpr_queue_ptr 0
		.amdhsa_user_sgpr_kernarg_segment_ptr 1
		.amdhsa_user_sgpr_dispatch_id 0
		.amdhsa_user_sgpr_kernarg_preload_length 0
		.amdhsa_user_sgpr_kernarg_preload_offset 0
		.amdhsa_user_sgpr_private_segment_size 0
		.amdhsa_uses_dynamic_stack 0
		.amdhsa_enable_private_segment 0
		.amdhsa_system_sgpr_workgroup_id_x 1
		.amdhsa_system_sgpr_workgroup_id_y 0
		.amdhsa_system_sgpr_workgroup_id_z 0
		.amdhsa_system_sgpr_workgroup_info 0
		.amdhsa_system_vgpr_workitem_id 2
		.amdhsa_next_free_vgpr 256
		.amdhsa_next_free_sgpr 102
		.amdhsa_accum_offset 256
		.amdhsa_reserve_vcc 1
		.amdhsa_float_round_mode_32 0
		.amdhsa_float_round_mode_16_64 0
		.amdhsa_float_denorm_mode_32 3
		.amdhsa_float_denorm_mode_16_64 3
		.amdhsa_dx10_clamp 1
		.amdhsa_ieee_mode 1
		.amdhsa_fp16_overflow 0
		.amdhsa_tg_split 0
		.amdhsa_exception_fp_ieee_invalid_op 0
		.amdhsa_exception_fp_denorm_src 0
		.amdhsa_exception_fp_ieee_div_zero 0
		.amdhsa_exception_fp_ieee_overflow 0
		.amdhsa_exception_fp_ieee_underflow 0
		.amdhsa_exception_fp_ieee_inexact 0
		.amdhsa_exception_int_div_zero 0
	.end_amdhsa_kernel

amdhsa.kernels:
  - .agpr_count:     0
    .args:
      - .offset:         0
        .size:           296
        .value_kind:     by_value
      - .offset:         296
        .size:           4
        .value_kind:     hidden_block_count_x
      - .offset:         300
        .size:           4
        .value_kind:     hidden_block_count_y
      - .offset:         304
        .size:           4
        .value_kind:     hidden_block_count_z
      - .offset:         308
        .size:           2
        .value_kind:     hidden_group_size_x
      - .offset:         310
        .size:           2
        .value_kind:     hidden_group_size_y
      - .offset:         312
        .size:           2
        .value_kind:     hidden_group_size_z
      - .offset:         314
        .size:           2
        .value_kind:     hidden_remainder_x
      - .offset:         316
        .size:           2
        .value_kind:     hidden_remainder_y
      - .offset:         318
        .size:           2
        .value_kind:     hidden_remainder_z
      - .offset:         336
        .size:           8
        .value_kind:     hidden_global_offset_x
      - .offset:         344
        .size:           8
        .value_kind:     hidden_global_offset_y
      - .offset:         352
        .size:           8
        .value_kind:     hidden_global_offset_z
      - .offset:         360
        .size:           2
        .value_kind:     hidden_grid_dims
      - .offset:         384
        .size:           8
        .value_kind:     hidden_multigrid_sync_arg
      - .offset:         416
        .size:           4
        .value_kind:     hidden_dynamic_lds_size
    .group_segment_fixed_size: 0
    .kernarg_segment_align: 8
    .kernarg_segment_size: 552
    .language:       OpenCL C
    .language_version:
      - 2
      - 0
    .max_flat_workgroup_size: 512
    .name:           _Z8mega_fwd4Args
    .private_segment_fixed_size: 0
    .sgpr_count:     108
    .sgpr_spill_count: 447
    .symbol:         _Z8mega_fwd4Args.kd
    .uniform_work_group_size: 1
    .uses_dynamic_stack: false
    .vgpr_count:     256
    .vgpr_spill_count: 0
    .wavefront_size: 64
